# v18 with the fused K-loop made protocol-safe: B1 fragment LDS reads are waited before the load-segment barrier, so the hoisted LDS-DMA into that slot is ordered behind every wave's reads
# speedup vs baseline: 1.0022x; 1.0022x over previous
; #define PG8_STAGE(bufoff, gbase, voff) do { _Pragma("unroll") for (int _i = 0; _i < 2; ++_i) \
;         __builtin_amdgcn_global_load_lds((const unsigned*)((const char*)(gbase) + (voff)[_i]), (LAS unsigned*)(lds + (bufoff) + ldsw + _i * 8192), 16, 0, 0); } while (0)
; #define PG8_LDA(dst, b, h) do { _Pragma("unroll") for (int m = 0; m < 4; ++m) _Pragma("unroll") for (int k = 0; k < 2; ++k) dst[m][k] = *(const LAS bf16x8*)(lds + PG8_SA(b, h) + aoff + m * 2048 + k * 1024); } while (0)
; #define PG8_LDB(dst, b, h) do { _Pragma("unroll") for (int n = 0; n < 2; ++n) _Pragma("unroll") for (int k = 0; k < 2; ++k) dst[n][k] = *(const LAS bf16x8*)(lds + PG8_SB(b, h) + boff + n * 2048 + k * 1024); } while (0)
; #define PG8_MMA(ai, bj, At, Bt) do { __builtin_amdgcn_s_setprio(1); _Pragma("unroll") for (int m = 0; m < 4; ++m) _Pragma("unroll") for (int n = 0; n < 2; ++n) _Pragma("unroll") for (int k = 0; k < 2; ++k) \
;         acc[ai][bj][m][n] = __builtin_amdgcn_mfma_f32_16x16x32_bf16(Bt[n][k], At[m][k], acc[ai][bj][m][n], 0, 0, 0); __builtin_amdgcn_s_setprio(0); } while (0)
; #define PG8_WAIT_V(n) asm volatile("s_waitcnt vmcnt(" #n ")" ::: "memory")
; #define PG8_WAIT_L(n) asm volatile("s_waitcnt lgkmcnt(" #n ")" ::: "memory")
; #define PG8_BAR __builtin_amdgcn_s_barrier()
; #define PG8_SCHED __builtin_amdgcn_sched_barrier(0)
; template <class Epi>
; __device__ __forceinline__ void gemm_phase(LAS unsigned char* lds, const Gemm g, const StaticOrder& S, const Epi& E, const int tidx) {
;     ...
;             PG8_LDB(B0, 0, 0); PG8_SCHED; PG8_LDA(At, 0, 0); PG8_STAGE(PG8_SA(1, 1), a1 + hstep, voffA);
;             PG8_WAIT_L(8); PG8_BAR; PG8_WAIT_L(0); PG8_MMA(0, 0, At, B0); PG8_BAR; PG8_SCHED;
;             PG8_LDB(B1, 0, 1); PG8_STAGE(PG8_SB(0, 0), b2, voffB);
;             PG8_BAR; PG8_WAIT_L(0); PG8_MMA(0, 1, At, B1); PG8_BAR;
;             PG8_LDA(At, 0, 1); PG8_STAGE(PG8_SA(0, 0), a2, voffA);
;             PG8_BAR; PG8_WAIT_L(0); PG8_MMA(1, 0, At, B0); PG8_BAR; PG8_SCHED;
;             PG8_STAGE(PG8_SB(0, 1), b2 + hstep, voffB);
;             PG8_WAIT_V(6); PG8_BAR; PG8_MMA(1, 1, At, B1); PG8_BAR;
.LBB0_713:
	s_add_i32 s8, s4, 2
	s_add_u32 s6, s2, 0x80
	s_addc_u32 s5, s3, 0
	s_add_i32 s9, 0, 0x10000
	v_add_u32_e32 v140, s9, v243
	s_waitcnt lgkmcnt(0)
	ds_read_b128 v[128:131], v140
	ds_read_b128 v[132:135], v140 offset:1024
	ds_read_b128 v[136:139], v140 offset:2048
	ds_read_b128 v[140:143], v140 offset:3072
	s_cmp_eq_u32 s59, s4
	s_cselect_b32 s4, s90, s6
	s_cselect_b32 s5, s91, s5
	s_cselect_b32 s7, s93, s1
	s_cselect_b32 s6, s92, s0
	v_lshl_add_u64 v[176:177], s[2:3], 0, v[206:207]
	s_add_i32 m0, s31, 0xc000
	ds_read_b128 v[144:147], v240
	ds_read_b128 v[148:151], v240 offset:1024
	ds_read_b128 v[152:155], v240 offset:2048
	ds_read_b128 v[156:159], v240 offset:3072
	ds_read_b128 v[160:163], v240 offset:4096
	ds_read_b128 v[164:167], v240 offset:5120
	ds_read_b128 v[168:171], v240 offset:6144
	ds_read_b128 v[172:175], v240 offset:7168
	global_load_lds_dwordx4 v[176:177], off
	v_lshl_add_u64 v[176:177], s[2:3], 0, v[208:209]
	s_add_i32 m0, s31, 0xe000
	s_nop 0
	global_load_lds_dwordx4 v[176:177], off
	s_waitcnt lgkmcnt(8)
	s_barrier
	s_waitcnt lgkmcnt(0)
	s_setprio 1
	s_waitcnt lgkmcnt(0)
	v_mfma_f32_16x16x32_bf16 v[116:119], v[128:131], v[144:147], v[116:119]
	v_mfma_f32_16x16x32_bf16 v[112:115], v[136:139], v[144:147], v[112:115]
	v_mfma_f32_16x16x32_bf16 v[100:103], v[128:131], v[152:155], v[100:103]
	v_mfma_f32_16x16x32_bf16 v[96:99], v[136:139], v[152:155], v[96:99]
	v_mfma_f32_16x16x32_bf16 v[84:87], v[128:131], v[160:163], v[84:87]
	v_mfma_f32_16x16x32_bf16 v[80:83], v[136:139], v[160:163], v[80:83]
	v_mfma_f32_16x16x32_bf16 v[68:71], v[128:131], v[168:171], v[68:71]
	v_mfma_f32_16x16x32_bf16 v[64:67], v[136:139], v[168:171], v[64:67]
	v_mfma_f32_16x16x32_bf16 v[116:119], v[132:135], v[148:151], v[116:119]
	v_mfma_f32_16x16x32_bf16 v[112:115], v[140:143], v[148:151], v[112:115]
	v_mfma_f32_16x16x32_bf16 v[100:103], v[132:135], v[156:159], v[100:103]
	v_mfma_f32_16x16x32_bf16 v[96:99], v[140:143], v[156:159], v[96:99]
	v_mfma_f32_16x16x32_bf16 v[84:87], v[132:135], v[164:167], v[84:87]
	v_mfma_f32_16x16x32_bf16 v[80:83], v[140:143], v[164:167], v[80:83]
	v_mfma_f32_16x16x32_bf16 v[68:71], v[132:135], v[172:175], v[68:71]
	v_mfma_f32_16x16x32_bf16 v[64:67], v[140:143], v[172:175], v[64:67]
	s_setprio 0
	s_barrier
	s_add_i32 s10, 0, 0x14000
	s_add_i32 s9, s9, s30
	v_add_u32_e32 v188, s10, v243
	v_lshl_add_u64 v[212:213], s[6:7], 0, v[202:203]
	s_mov_b32 m0, s9
	ds_read_b128 v[176:179], v188
	ds_read_b128 v[180:183], v188 offset:1024
	ds_read_b128 v[184:187], v188 offset:2048
	ds_read_b128 v[188:191], v188 offset:3072
	global_load_lds_dwordx4 v[212:213], off
	v_lshl_add_u64 v[214:215], s[6:7], 0, v[198:199]
	s_add_i32 m0, s9, 0x2000
	s_nop 0
	global_load_lds_dwordx4 v[214:215], off
	s_waitcnt lgkmcnt(0)
	s_barrier
	s_waitcnt lgkmcnt(0)
	s_setprio 1
	s_waitcnt lgkmcnt(0)
	v_mfma_f32_16x16x32_bf16 v[124:127], v[176:179], v[144:147], v[124:127]
	v_mfma_f32_16x16x32_bf16 v[120:123], v[184:187], v[144:147], v[120:123]
	v_mfma_f32_16x16x32_bf16 v[108:111], v[176:179], v[152:155], v[108:111]
	v_mfma_f32_16x16x32_bf16 v[104:107], v[184:187], v[152:155], v[104:107]
	v_mfma_f32_16x16x32_bf16 v[92:95], v[176:179], v[160:163], v[92:95]
	v_mfma_f32_16x16x32_bf16 v[88:91], v[184:187], v[160:163], v[88:91]
	v_mfma_f32_16x16x32_bf16 v[76:79], v[176:179], v[168:171], v[76:79]
	v_mfma_f32_16x16x32_bf16 v[72:75], v[184:187], v[168:171], v[72:75]
	v_mfma_f32_16x16x32_bf16 v[124:127], v[180:183], v[148:151], v[124:127]
	v_mfma_f32_16x16x32_bf16 v[120:123], v[188:191], v[148:151], v[120:123]
	v_mfma_f32_16x16x32_bf16 v[108:111], v[180:183], v[156:159], v[108:111]
	v_mfma_f32_16x16x32_bf16 v[104:107], v[188:191], v[156:159], v[104:107]
	v_mfma_f32_16x16x32_bf16 v[92:95], v[180:183], v[164:167], v[92:95]
	v_mfma_f32_16x16x32_bf16 v[88:91], v[188:191], v[164:167], v[88:91]
	v_mfma_f32_16x16x32_bf16 v[76:79], v[180:183], v[172:175], v[76:79]
	v_mfma_f32_16x16x32_bf16 v[72:75], v[188:191], v[172:175], v[72:75]
	s_setprio 0
	s_mov_b32 m0, s31
	v_lshl_add_u64 v[216:217], s[4:5], 0, v[200:201]
	s_barrier
	ds_read_b128 v[144:147], v240 offset:16384
	ds_read_b128 v[148:151], v240 offset:17408
	ds_read_b128 v[152:155], v240 offset:18432
	ds_read_b128 v[156:159], v240 offset:19456
	ds_read_b128 v[160:163], v240 offset:20480
	ds_read_b128 v[164:167], v240 offset:21504
	ds_read_b128 v[168:171], v240 offset:22528
	ds_read_b128 v[172:175], v240 offset:23552
	global_load_lds_dwordx4 v[216:217], off
	v_lshl_add_u64 v[218:219], s[4:5], 0, v[196:197]
	s_mov_b32 m0, s34
	s_nop 0
	global_load_lds_dwordx4 v[218:219], off
	s_add_u32 s6, s6, s14
	s_addc_u32 s7, s7, 0
	s_add_i32 s9, s10, s30
	v_lshl_add_u64 v[220:221], s[6:7], 0, v[202:203]
	s_mov_b32 m0, s9
	v_lshl_add_u64 v[222:223], s[6:7], 0, v[198:199]
	global_load_lds_dwordx4 v[220:221], off
	s_add_i32 m0, s9, 0x2000
	s_nop 0
	global_load_lds_dwordx4 v[222:223], off
	s_waitcnt vmcnt(6)
	s_barrier
	s_waitcnt lgkmcnt(0)
	s_setprio 1
	s_waitcnt lgkmcnt(0)
	s_cmp_eq_u32 s13, 0x80
	s_cbranch_scc1 .Lskip_mma_2
; #define PG8_STAGE(bufoff, gbase, voff) do { _Pragma("unroll") for (int _i = 0; _i < 2; ++_i) \
;         __builtin_amdgcn_global_load_lds((const unsigned*)((const char*)(gbase) + (voff)[_i]), (LAS unsigned*)(lds + (bufoff) + ldsw + _i * 8192), 16, 0, 0); } while (0)
; #define PG8_MMA(ai, bj, At, Bt) do { __builtin_amdgcn_s_setprio(1); _Pragma("unroll") for (int m = 0; m < 4; ++m) _Pragma("unroll") for (int n = 0; n < 2; ++n) _Pragma("unroll") for (int k = 0; k < 2; ++k) \
;         acc[ai][bj][m][n] = __builtin_amdgcn_mfma_f32_16x16x32_bf16(Bt[n][k], At[m][k], acc[ai][bj][m][n], 0, 0, 0); __builtin_amdgcn_s_setprio(0); } while (0)
; #define PG8_WAIT_V(n) asm volatile("s_waitcnt vmcnt(" #n ")" ::: "memory")
; #define PG8_WAIT_L(n) asm volatile("s_waitcnt lgkmcnt(" #n ")" ::: "memory")
; #define PG8_BAR __builtin_amdgcn_s_barrier()
; #define PG8_SCHED __builtin_amdgcn_sched_barrier(0)
; template <class Epi>
; __device__ __forceinline__ void gemm_phase(LAS unsigned char* lds, const Gemm g, const StaticOrder& S, const Epi& E, const int tidx) {
;     ...
;             PG8_BAR; PG8_WAIT_L(0); PG8_MMA(1, 0, At, B0); PG8_BAR; PG8_SCHED;
;             PG8_STAGE(PG8_SB(0, 1), b2 + hstep, voffB);
;             PG8_WAIT_V(6); PG8_BAR; PG8_MMA(1, 1, At, B1); PG8_BAR;
	v_mfma_f32_16x16x32_bf16 v[52:55], v[128:131], v[144:147], v[52:55]
	v_mfma_f32_16x16x32_bf16 v[48:51], v[136:139], v[144:147], v[48:51]
	v_mfma_f32_16x16x32_bf16 v[36:39], v[128:131], v[152:155], v[36:39]
	v_mfma_f32_16x16x32_bf16 v[32:35], v[136:139], v[152:155], v[32:35]
	v_mfma_f32_16x16x32_bf16 v[20:23], v[128:131], v[160:163], v[20:23]
	v_mfma_f32_16x16x32_bf16 v[16:19], v[136:139], v[160:163], v[16:19]
	v_mfma_f32_16x16x32_bf16 v[4:7], v[128:131], v[168:171], v[4:7]
	v_mfma_f32_16x16x32_bf16 v[0:3], v[136:139], v[168:171], v[0:3]
	v_mfma_f32_16x16x32_bf16 v[52:55], v[132:135], v[148:151], v[52:55]
	v_mfma_f32_16x16x32_bf16 v[48:51], v[140:143], v[148:151], v[48:51]
	v_mfma_f32_16x16x32_bf16 v[36:39], v[132:135], v[156:159], v[36:39]
	v_mfma_f32_16x16x32_bf16 v[32:35], v[140:143], v[156:159], v[32:35]
	v_mfma_f32_16x16x32_bf16 v[20:23], v[132:135], v[164:167], v[20:23]
	v_mfma_f32_16x16x32_bf16 v[16:19], v[140:143], v[164:167], v[16:19]
	v_mfma_f32_16x16x32_bf16 v[4:7], v[132:135], v[172:175], v[4:7]
	v_mfma_f32_16x16x32_bf16 v[0:3], v[140:143], v[172:175], v[0:3]
	v_mfma_f32_16x16x32_bf16 v[60:63], v[176:179], v[144:147], v[60:63]
	v_mfma_f32_16x16x32_bf16 v[56:59], v[184:187], v[144:147], v[56:59]
	v_mfma_f32_16x16x32_bf16 v[44:47], v[176:179], v[152:155], v[44:47]
	v_mfma_f32_16x16x32_bf16 v[40:43], v[184:187], v[152:155], v[40:43]
	v_mfma_f32_16x16x32_bf16 v[28:31], v[176:179], v[160:163], v[28:31]
	v_mfma_f32_16x16x32_bf16 v[24:27], v[184:187], v[160:163], v[24:27]
	v_mfma_f32_16x16x32_bf16 v[12:15], v[176:179], v[168:171], v[12:15]
	v_mfma_f32_16x16x32_bf16 v[8:11], v[184:187], v[168:171], v[8:11]
	v_mfma_f32_16x16x32_bf16 v[60:63], v[180:183], v[148:151], v[60:63]
	v_mfma_f32_16x16x32_bf16 v[56:59], v[188:191], v[148:151], v[56:59]
	v_mfma_f32_16x16x32_bf16 v[44:47], v[180:183], v[156:159], v[44:47]
	v_mfma_f32_16x16x32_bf16 v[40:43], v[188:191], v[156:159], v[40:43]
	v_mfma_f32_16x16x32_bf16 v[28:31], v[180:183], v[164:167], v[28:31]
	v_mfma_f32_16x16x32_bf16 v[24:27], v[188:191], v[164:167], v[24:27]
	v_mfma_f32_16x16x32_bf16 v[12:15], v[180:183], v[172:175], v[12:15]
	v_mfma_f32_16x16x32_bf16 v[8:11], v[188:191], v[172:175], v[8:11]
; #define PG8_STAGE(bufoff, gbase, voff) do { _Pragma("unroll") for (int _i = 0; _i < 2; ++_i) \
;         __builtin_amdgcn_global_load_lds((const unsigned*)((const char*)(gbase) + (voff)[_i]), (LAS unsigned*)(lds + (bufoff) + ldsw + _i * 8192), 16, 0, 0); } while (0)
; #define PG8_LDA(dst, b, h) do { _Pragma("unroll") for (int m = 0; m < 4; ++m) _Pragma("unroll") for (int k = 0; k < 2; ++k) dst[m][k] = *(const LAS bf16x8*)(lds + PG8_SA(b, h) + aoff + m * 2048 + k * 1024); } while (0)
; #define PG8_LDB(dst, b, h) do { _Pragma("unroll") for (int n = 0; n < 2; ++n) _Pragma("unroll") for (int k = 0; k < 2; ++k) dst[n][k] = *(const LAS bf16x8*)(lds + PG8_SB(b, h) + boff + n * 2048 + k * 1024); } while (0)
; #define PG8_MMA(ai, bj, At, Bt) do { __builtin_amdgcn_s_setprio(1); _Pragma("unroll") for (int m = 0; m < 4; ++m) _Pragma("unroll") for (int n = 0; n < 2; ++n) _Pragma("unroll") for (int k = 0; k < 2; ++k) \
;         acc[ai][bj][m][n] = __builtin_amdgcn_mfma_f32_16x16x32_bf16(Bt[n][k], At[m][k], acc[ai][bj][m][n], 0, 0, 0); __builtin_amdgcn_s_setprio(0); } while (0)
; #define PG8_WAIT_V(n) asm volatile("s_waitcnt vmcnt(" #n ")" ::: "memory")
; #define PG8_WAIT_L(n) asm volatile("s_waitcnt lgkmcnt(" #n ")" ::: "memory")
; #define PG8_BAR __builtin_amdgcn_s_barrier()
; #define PG8_SCHED __builtin_amdgcn_sched_barrier(0)
; template <class Epi>
; __device__ __forceinline__ void gemm_phase(LAS unsigned char* lds, const Gemm g, const StaticOrder& S, const Epi& E, const int tidx) {
;     ...
;             PG8_LDB(B0, 1, 0); PG8_SCHED; PG8_LDA(At, 1, 0); PG8_STAGE(PG8_SA(0, 1), a2 + hstep, voffA);
;             PG8_WAIT_L(8); PG8_BAR; PG8_WAIT_L(0); PG8_MMA(0, 0, At, B0); PG8_BAR; PG8_SCHED;
;             PG8_LDB(B1, 1, 1); PG8_STAGE(PG8_SB(1, 0), b3, voffB);
;             PG8_BAR; PG8_WAIT_L(0); PG8_MMA(0, 1, At, B1); PG8_BAR;
;             PG8_LDA(At, 1, 1); PG8_STAGE(PG8_SA(1, 0), a3, voffA);
;             PG8_BAR; PG8_WAIT_L(0); PG8_MMA(1, 0, At, B0); PG8_BAR; PG8_SCHED;
;             PG8_STAGE(PG8_SB(1, 1), b3 + hstep, voffB);
;             PG8_WAIT_V(6); PG8_BAR; PG8_MMA(1, 1, At, B1); PG8_BAR;
.Lskip_mma_2:
.Lskip_mma_3:
	s_setprio 0
	s_add_i32 s6, 0, 0x18000
	v_add_u32_e32 v140, s6, v243
	s_barrier
	ds_read_b128 v[128:131], v140
	ds_read_b128 v[132:135], v140 offset:1024
	ds_read_b128 v[136:139], v140 offset:2048
	ds_read_b128 v[140:143], v140 offset:3072
	s_add_u32 s4, s4, s14
	s_addc_u32 s5, s5, 0
	s_mov_b32 m0, s35
	v_lshl_add_u64 v[176:177], s[4:5], 0, v[200:201]
	ds_read_b128 v[144:147], v240 offset:32768
	ds_read_b128 v[148:151], v240 offset:33792
	ds_read_b128 v[152:155], v240 offset:34816
	ds_read_b128 v[156:159], v240 offset:35840
	ds_read_b128 v[160:163], v240 offset:36864
	ds_read_b128 v[164:167], v240 offset:37888
	ds_read_b128 v[168:171], v240 offset:38912
	ds_read_b128 v[172:175], v240 offset:39936
	global_load_lds_dwordx4 v[176:177], off
	v_lshl_add_u64 v[176:177], s[4:5], 0, v[196:197]
	s_mov_b32 m0, s54
	s_nop 0
	global_load_lds_dwordx4 v[176:177], off
	s_waitcnt lgkmcnt(8)
	s_barrier
	s_waitcnt lgkmcnt(0)
	s_setprio 1
	s_waitcnt lgkmcnt(0)
	v_mfma_f32_16x16x32_bf16 v[116:119], v[128:131], v[144:147], v[116:119]
	v_mfma_f32_16x16x32_bf16 v[112:115], v[136:139], v[144:147], v[112:115]
	v_mfma_f32_16x16x32_bf16 v[100:103], v[128:131], v[152:155], v[100:103]
	v_mfma_f32_16x16x32_bf16 v[96:99], v[136:139], v[152:155], v[96:99]
	v_mfma_f32_16x16x32_bf16 v[84:87], v[128:131], v[160:163], v[84:87]
	v_mfma_f32_16x16x32_bf16 v[80:83], v[136:139], v[160:163], v[80:83]
	v_mfma_f32_16x16x32_bf16 v[68:71], v[128:131], v[168:171], v[68:71]
	v_mfma_f32_16x16x32_bf16 v[64:67], v[136:139], v[168:171], v[64:67]
	v_mfma_f32_16x16x32_bf16 v[116:119], v[132:135], v[148:151], v[116:119]
	v_mfma_f32_16x16x32_bf16 v[112:115], v[140:143], v[148:151], v[112:115]
	v_mfma_f32_16x16x32_bf16 v[100:103], v[132:135], v[156:159], v[100:103]
	v_mfma_f32_16x16x32_bf16 v[96:99], v[140:143], v[156:159], v[96:99]
	v_mfma_f32_16x16x32_bf16 v[84:87], v[132:135], v[164:167], v[84:87]
	v_mfma_f32_16x16x32_bf16 v[80:83], v[140:143], v[164:167], v[80:83]
	v_mfma_f32_16x16x32_bf16 v[68:71], v[132:135], v[172:175], v[68:71]
	v_mfma_f32_16x16x32_bf16 v[64:67], v[140:143], v[172:175], v[64:67]
	s_setprio 0
	s_barrier
	s_add_i32 s4, 0, 0x1c000
	s_add_i32 s5, s6, s30
	v_add_u32_e32 v188, s4, v243
	v_lshl_add_u64 v[212:213], v[212:213], 0, s[16:17]
	s_mov_b32 m0, s5
	ds_read_b128 v[176:179], v188
	ds_read_b128 v[180:183], v188 offset:1024
	ds_read_b128 v[184:187], v188 offset:2048
	ds_read_b128 v[188:191], v188 offset:3072
	global_load_lds_dwordx4 v[212:213], off
	v_lshl_add_u64 v[212:213], v[214:215], 0, s[16:17]
	s_add_i32 m0, s5, 0x2000
	s_nop 0
	global_load_lds_dwordx4 v[212:213], off
	s_waitcnt lgkmcnt(0)
	s_barrier
	s_waitcnt lgkmcnt(0)
	s_setprio 1
	s_waitcnt lgkmcnt(0)
	v_mfma_f32_16x16x32_bf16 v[124:127], v[176:179], v[144:147], v[124:127]
	v_mfma_f32_16x16x32_bf16 v[120:123], v[184:187], v[144:147], v[120:123]
	v_mfma_f32_16x16x32_bf16 v[108:111], v[176:179], v[152:155], v[108:111]
	v_mfma_f32_16x16x32_bf16 v[104:107], v[184:187], v[152:155], v[104:107]
	v_mfma_f32_16x16x32_bf16 v[92:95], v[176:179], v[160:163], v[92:95]
	v_mfma_f32_16x16x32_bf16 v[88:91], v[184:187], v[160:163], v[88:91]
	v_mfma_f32_16x16x32_bf16 v[76:79], v[176:179], v[168:171], v[76:79]
	v_mfma_f32_16x16x32_bf16 v[72:75], v[184:187], v[168:171], v[72:75]
	v_mfma_f32_16x16x32_bf16 v[124:127], v[180:183], v[148:151], v[124:127]
	v_mfma_f32_16x16x32_bf16 v[120:123], v[188:191], v[148:151], v[120:123]
	v_mfma_f32_16x16x32_bf16 v[108:111], v[180:183], v[156:159], v[108:111]
	v_mfma_f32_16x16x32_bf16 v[104:107], v[188:191], v[156:159], v[104:107]
	v_mfma_f32_16x16x32_bf16 v[92:95], v[180:183], v[164:167], v[92:95]
	v_mfma_f32_16x16x32_bf16 v[88:91], v[188:191], v[164:167], v[88:91]
	v_mfma_f32_16x16x32_bf16 v[76:79], v[180:183], v[172:175], v[76:79]
	v_mfma_f32_16x16x32_bf16 v[72:75], v[188:191], v[172:175], v[72:75]
	s_setprio 0
	s_mov_b32 m0, s57
	v_lshl_add_u64 v[212:213], v[216:217], 0, s[16:17]
	s_barrier
	ds_read_b128 v[144:147], v240 offset:49152
	ds_read_b128 v[148:151], v240 offset:50176
	ds_read_b128 v[152:155], v240 offset:51200
	ds_read_b128 v[156:159], v240 offset:52224
	ds_read_b128 v[160:163], v240 offset:53248
	ds_read_b128 v[164:167], v240 offset:54272
	ds_read_b128 v[168:171], v240 offset:55296
	ds_read_b128 v[172:175], v240 offset:56320
	global_load_lds_dwordx4 v[212:213], off
	v_lshl_add_u64 v[212:213], v[218:219], 0, s[16:17]
	s_mov_b32 m0, s58
	s_nop 0
	global_load_lds_dwordx4 v[212:213], off
	s_add_i32 s4, s4, s30
	v_lshl_add_u64 v[212:213], v[220:221], 0, s[16:17]
	s_mov_b32 m0, s4
	s_nop 0
	global_load_lds_dwordx4 v[212:213], off
	v_lshl_add_u64 v[212:213], v[222:223], 0, s[16:17]
	s_add_i32 m0, s4, 0x2000
	s_nop 0
	global_load_lds_dwordx4 v[212:213], off
	s_waitcnt vmcnt(6)
	s_barrier
	s_waitcnt lgkmcnt(0)
	s_setprio 1
	s_waitcnt lgkmcnt(0)
	s_cmp_eq_u32 s13, 0x80
	s_cbranch_scc1 .Lskip_mma_6
	v_mfma_f32_16x16x32_bf16 v[52:55], v[128:131], v[144:147], v[52:55]
	v_mfma_f32_16x16x32_bf16 v[48:51], v[136:139], v[144:147], v[48:51]
	v_mfma_f32_16x16x32_bf16 v[36:39], v[128:131], v[152:155], v[36:39]
	v_mfma_f32_16x16x32_bf16 v[32:35], v[136:139], v[152:155], v[32:35]
	v_mfma_f32_16x16x32_bf16 v[20:23], v[128:131], v[160:163], v[20:23]
	v_mfma_f32_16x16x32_bf16 v[16:19], v[136:139], v[160:163], v[16:19]
	v_mfma_f32_16x16x32_bf16 v[4:7], v[128:131], v[168:171], v[4:7]
	v_mfma_f32_16x16x32_bf16 v[0:3], v[136:139], v[168:171], v[0:3]
	v_mfma_f32_16x16x32_bf16 v[52:55], v[132:135], v[148:151], v[52:55]
	v_mfma_f32_16x16x32_bf16 v[48:51], v[140:143], v[148:151], v[48:51]
	v_mfma_f32_16x16x32_bf16 v[36:39], v[132:135], v[156:159], v[36:39]
	v_mfma_f32_16x16x32_bf16 v[32:35], v[140:143], v[156:159], v[32:35]
	v_mfma_f32_16x16x32_bf16 v[20:23], v[132:135], v[164:167], v[20:23]
	v_mfma_f32_16x16x32_bf16 v[16:19], v[140:143], v[164:167], v[16:19]
	v_mfma_f32_16x16x32_bf16 v[4:7], v[132:135], v[172:175], v[4:7]
	v_mfma_f32_16x16x32_bf16 v[0:3], v[140:143], v[172:175], v[0:3]
	v_mfma_f32_16x16x32_bf16 v[60:63], v[176:179], v[144:147], v[60:63]
	v_mfma_f32_16x16x32_bf16 v[56:59], v[184:187], v[144:147], v[56:59]
	v_mfma_f32_16x16x32_bf16 v[44:47], v[176:179], v[152:155], v[44:47]
	v_mfma_f32_16x16x32_bf16 v[40:43], v[184:187], v[152:155], v[40:43]
	v_mfma_f32_16x16x32_bf16 v[28:31], v[176:179], v[160:163], v[28:31]
	v_mfma_f32_16x16x32_bf16 v[24:27], v[184:187], v[160:163], v[24:27]
	v_mfma_f32_16x16x32_bf16 v[12:15], v[176:179], v[168:171], v[12:15]
	v_mfma_f32_16x16x32_bf16 v[8:11], v[184:187], v[168:171], v[8:11]
	v_mfma_f32_16x16x32_bf16 v[60:63], v[180:183], v[148:151], v[60:63]
	v_mfma_f32_16x16x32_bf16 v[56:59], v[188:191], v[148:151], v[56:59]
	v_mfma_f32_16x16x32_bf16 v[44:47], v[180:183], v[156:159], v[44:47]
	v_mfma_f32_16x16x32_bf16 v[40:43], v[188:191], v[156:159], v[40:43]
	v_mfma_f32_16x16x32_bf16 v[28:31], v[180:183], v[164:167], v[28:31]
	v_mfma_f32_16x16x32_bf16 v[24:27], v[188:191], v[164:167], v[24:27]
	v_mfma_f32_16x16x32_bf16 v[12:15], v[180:183], v[172:175], v[12:15]
	v_mfma_f32_16x16x32_bf16 v[8:11], v[188:191], v[172:175], v[8:11]
